# stack + workgroups idle in the last in-proj round poll their XCD arrival counter slowly (s_sleep 40) until all but 2 local workgroups have arrived, then poll the release word at full rate
# speedup vs baseline: 1.0166x; 1.0166x over previous
; __device__ __forceinline__ unsigned xb_ld(unsigned* p)              { return __hip_atomic_load(p, __ATOMIC_RELAXED, __HIP_MEMORY_SCOPE_AGENT); }
; __device__ __forceinline__ unsigned xb_add(unsigned* p, unsigned v) { return __hip_atomic_fetch_add(p, v, __ATOMIC_RELAXED, __HIP_MEMORY_SCOPE_AGENT); }
; #define XB_SPIN(cond, bar) do { unsigned _sp = 0; while (cond) { __builtin_amdgcn_s_sleep(1); \
;     if ((++_sp & 255u) == 0u) { if (xb_ld(&(bar)[XB_TMO])) break; if (_sp > XB_SPIN_CAP) { atomicAdd(&(bar)[XB_TMO], 1u); break; } } } } while (0)
; __device__ __forceinline__ void xcd_barrier(const XcdBarrier& b) {
;     asm volatile("s_waitcnt vmcnt(0)" ::: "memory");
;     __syncthreads();
;     if (threadIdx.x == 0) {
;         unsigned* bar = b.bar;
;         __builtin_amdgcn_s_waitcnt(0);
;         unsigned nloc = b.st[0], nx = b.st[1];
;         if (nloc == 0u) { xcd_barrier_complete(bar, b.x, nloc, nx); b.st[0] = nloc; b.st[1] = nx; }
;         const unsigned old = xb_add(&bar[XB_XSUB(b.x)], 1u);
;         const unsigned gen = old / nloc;
;         if (old + 1u == (gen + 1u) * nloc) {
;             __builtin_amdgcn_fence(__ATOMIC_RELEASE, "agent");
;             asm volatile("s_waitcnt vmcnt(0)" ::: "memory");
;             const unsigned og = xb_add(&bar[XB_TOP], 1u);
;             const unsigned tg = og / nx;
;             if (og + 1u == (tg + 1u) * nx) xb_add(&bar[XB_TOPGEN], 1u);
;             else XB_SPIN(xb_ld(&bar[XB_TOPGEN]) == tg, bar);
;             __builtin_amdgcn_fence(__ATOMIC_ACQUIRE, "agent");
;             xb_add(&bar[XB_XGEN(b.x)], 1u);
;             asm volatile("s_waitcnt vmcnt(0)" ::: "memory");
;         } else {
;             XB_SPIN(xb_ld(&bar[XB_XGEN(b.x)]) == gen, bar);
;             __builtin_amdgcn_fence(__ATOMIC_ACQUIRE, "agent");
;             asm volatile("s_waitcnt vmcnt(0)" ::: "memory");
;         }
.Lxb_local_i:
	s_cmp_lg_u32 s42, 0x100
	s_cbranch_scc1 .Lxb_sp_done
	s_cmp_lt_u32 s71, 0x74
	s_cbranch_scc1 .Lxb_sp_done
	s_sub_i32 s4, s5, 2
	s_mov_b32 s3, 0
.Lxb_sp_loop:
	s_sleep 40
	global_load_dword v2, v173, s[6:7] sc1
	s_waitcnt vmcnt(0)
	v_readfirstlane_b32 s5, v2
	s_nop 3
	s_cmp_ge_u32 s5, s4
	s_cbranch_scc1 .Lxb_sp_done
	s_add_i32 s3, s3, 1
	s_cmp_lt_u32 s3, 0x4000
	s_cbranch_scc1 .Lxb_sp_loop
